# attention loop v2 + one static s_setprio 1 for waves 4-7 around the K-tile loop
# speedup vs baseline: 1.0074x; 1.0074x over previous
; template <bool SHIFT> DI void attn_unit(LAS unsigned char* lds, const bf16_t* Qb, const bf16_t* Kb, const bf16_t* Vt, bf16_t* concat,
;                   int b, int h, int qt, float shift2, float lam, int lam_init_bits, const float* subln_g) {
;     const int tid = TID(), wid = __builtin_amdgcn_readfirstlane(tid >> 6), lane = tid & 63, r = lane & 31, hh = lane >> 5;
;     const size_t rowbase = (size_t)b * TPB;
;     const int q0 = qt * 256;
;     const int nkt = (qt == 0) ? 4 : NCH;
;     const bf16_t* kg = Kb + rowbase * 1024 + h * 128;
;     const bf16_t* vg = Vt + ((size_t)(b * 8 + h) * 128) * TPB;
;     const int krow0 = tid >> 4, kc = tid & 15;
;     const int vrow0 = tid >> 3, vc = tid & 7;
; #pragma unroll
;     for (int i = 0; i < 8; ++i) { const int id = i * 512 + tid, row = id >> 4, c = id & 15;
;         const u32x4 v = *(const u32x4*)(Qb + (rowbase + q0 + row) * 1024 + h * 128 + c * 8);
;         *(LAS u32x4*)(lds + Q_OFF + row * QP + c * 16) = v; }
;     u32x4 sg0, sg1;
;     sg0 = *(const u32x4*)(kg + (size_t)(krow0) * 1024 + kc * 8); sg1 = *(const u32x4*)(kg + (size_t)(krow0 + 32) * 1024 + kc * 8);
;     *(LAS u32x4*)(lds + K_OFF + krow0 * QP + kc * 16) = sg0; *(LAS u32x4*)(lds + K_OFF + (krow0 + 32) * QP + kc * 16) = sg1;
;     sg0 = *(const u32x4*)(vg + (size_t)(vrow0) * TPB + vc * 8); sg1 = *(const u32x4*)(vg + (size_t)(vrow0 + 64) * TPB + vc * 8);
;     *(LAS u32x4*)(lds + V_OFF + vrow0 * VP + vc * 16) = sg0; *(LAS u32x4*)(lds + V_OFF + (vrow0 + 64) * VP + vc * 16) = sg1;
;     if (nkt > 1) { sg0 = *(const u32x4*)(kg + (size_t)(64 + krow0) * 1024 + kc * 8); sg1 = *(const u32x4*)(kg + (size_t)(64 + krow0 + 32) * 1024 + kc * 8); }
;     __syncthreads();
;     f32x16 OT[2][4];
; #pragma unroll
;     for (int m = 0; m < 2; ++m)
; #pragma unroll
;         for (int t = 0; t < 4; ++t)
; #pragma unroll
;             for (int i = 0; i < 16; ++i) OT[m][t][i] = 0.f;
;     float lsum[2] = {0.f, 0.f};
;     const LAS unsigned char* qrow = lds + Q_OFF + (32 * wid + r) * QP + hh * 16;
;     ...
;     const bool lag = wid >= 4;
;     bf16x8 Pc[2][2];
; #pragma unroll
;     for (int m = 0; m < 2; ++m)
; #pragma unroll
;         for (int g = 0; g < 2; ++g) { u32x4 z = {0u, 0u, 0u, 0u}; Pc[m][g] = __builtin_bit_cast(bf16x8, z); }
;     const LAS unsigned char* vold = lds + V_OFF + r * VP + hh * 16;
;     int vcur = 0;
.LBB0_532:
	s_mov_b64 s[4:5], s[0:1]
	s_load_dwordx2 s[20:21], s[4:5], 0xa8
	s_mov_b64 s[4:5], s[0:1]
	s_waitcnt lgkmcnt(0)
	s_load_dwordx2 s[4:5], s[4:5], 0xa8
	s_and_b32 s30, s6, 7
	s_mov_b64 s[6:7], s[0:1]
	s_waitcnt lgkmcnt(0)
	s_load_dwordx2 s[6:7], s[6:7], 0xa8
	s_mov_b64 s[12:13], s[0:1]
	s_waitcnt lgkmcnt(0)
	s_mov_b64 s[14:15], s[0:1]
	s_load_dwordx2 s[12:13], s[12:13], 0xa8
	v_mov_b32_e32 v16, v222
	s_lshl_b32 s18, s22, 3
	s_waitcnt lgkmcnt(0)
	s_load_dwordx2 s[16:17], s[14:15], 0x60
	s_or_b32 s34, s18, s30
	v_readfirstlane_b32 s14, v16
	s_lshl_b32 s37, s23, 8
	s_lshl_b32 s29, s30, 7
	s_ashr_i32 s31, s14, 6
	s_mul_i32 s15, s34, 0x210000
	s_mul_hi_i32 s14, s34, 0x210000
	s_add_u32 s15, s6, s15
	s_addc_u32 s14, s7, s14
	s_add_u32 s18, s15, 0x10788000
	s_mul_i32 s36, s22, 0x2100
	s_addc_u32 s19, s14, 0
	s_mul_hi_i32 s35, s22, 0x2100
	s_add_u32 s14, s36, s37
	s_addc_u32 s15, s35, 0
	s_lshl_b32 s37, s30, 8
	s_add_u32 s20, s20, s37
	v_and_b32_e32 v17, 15, v16
	s_addc_u32 s21, s21, 0
	v_lshlrev_b32_e32 v160, 4, v17
	v_mov_b32_e32 v161, v177
	v_ashrrev_i32_e32 v6, 4, v16
	v_lshl_add_u64 v[0:1], s[20:21], 0, v[160:161]
	s_mov_b64 s[20:21], 0xa488000
	v_ashrrev_i32_e32 v7, 31, v6
	v_lshl_add_u64 v[4:5], v[0:1], 0, s[20:21]
	v_lshl_add_u64 v[0:1], s[14:15], 0, v[6:7]
	v_lshlrev_b64 v[0:1], 11, v[0:1]
	v_lshl_add_u64 v[0:1], v[4:5], 0, v[0:1]
	global_load_dwordx4 v[32:35], v[0:1], off
	s_mov_b64 s[20:21], 0x10000
	v_lshl_add_u64 v[64:65], v[0:1], 0, s[20:21]
	global_load_dwordx4 v[36:39], v[64:65], off
	v_lshl_add_u64 v[64:65], v[64:65], 0, s[20:21]
	global_load_dwordx4 v[40:43], v[64:65], off
	v_lshl_add_u64 v[64:65], v[64:65], 0, s[20:21]
	global_load_dwordx4 v[44:47], v[64:65], off
	v_lshl_add_u64 v[64:65], v[64:65], 0, s[20:21]
	global_load_dwordx4 v[48:51], v[64:65], off
	v_lshl_add_u64 v[64:65], v[64:65], 0, s[20:21]
	global_load_dwordx4 v[52:55], v[64:65], off
	v_lshl_add_u64 v[64:65], v[64:65], 0, s[20:21]
	global_load_dwordx4 v[56:59], v[64:65], off
	v_lshl_add_u64 v[64:65], v[64:65], 0, s[20:21]
	global_load_dwordx4 v[60:63], v[64:65], off
	v_add_u32_e32 v8, 0x200, v16
	v_ashrrev_i32_e32 v8, 4, v8
	v_ashrrev_i32_e32 v9, 31, v8
	v_mul_lo_u32 v210, v6, s54
	v_add_u32_e32 v10, 0, v160
	v_lshl_add_u64 v[12:13], s[14:15], 0, v[8:9]
	v_add_u32_e32 v11, v10, v210
	v_mov_b32_e32 v82, v11
	v_lshlrev_b64 v[12:13], 11, v[12:13]
	v_lshl_add_u64 v[12:13], v[4:5], 0, v[12:13]
	v_add_u32_e32 v9, 0x400, v16
	s_mul_i32 s35, s22, 0x1080000
	s_mul_hi_i32 s30, s22, 0x1080000
	v_ashrrev_i32_e32 v18, 3, v16
	v_add_u32_e32 v19, 64, v18
	v_add3_u32 v20, s47, v210, v160
	v_add_u32_e32 v214, 0x2200, v210
	v_add3_u32 v21, s47, v214, v160
	v_mul_lo_u32 v215, v18, s44
	v_add_u32_e32 v216, 0x2400, v215
	v_bfe_u32 v236, v16, 5, 1
	v_lshlrev_b32_e32 v163, 4, v236
	v_lshlrev_b32_e32 v162, 3, v17
	v_mov_b32_e32 v164, 0
	v_mov_b32_e32 v128, 0
	v_mov_b32_e32 v129, 0
	v_mov_b32_e32 v130, 0
	v_mov_b32_e32 v131, 0
	v_mov_b32_e32 v132, 0
	v_mov_b32_e32 v133, 0
	v_mov_b32_e32 v134, 0
	v_mov_b32_e32 v135, 0
	v_mov_b32_e32 v152, 0
	v_mov_b32_e32 v153, 0
	v_mov_b32_e32 v154, 0
	v_mov_b32_e32 v155, 0
	v_mov_b32_e32 v156, 0
	v_mov_b32_e32 v157, 0
	v_mov_b32_e32 v158, 0
	v_mov_b32_e32 v159, 0
	v_mov_b32_e32 v165, v164
	v_ashrrev_i32_e32 v12, 4, v9
	v_ashrrev_i32_e32 v13, 31, v12
	v_lshl_add_u64 v[14:15], s[14:15], 0, v[12:13]
	v_mad_u64_u32 v[8:9], s[20:21], v8, s54, v[10:11]
	v_lshlrev_b64 v[14:15], 11, v[14:15]
	v_lshl_add_u64 v[14:15], v[4:5], 0, v[14:15]
	v_mad_u64_u32 v[12:13], s[20:21], v12, s54, v[10:11]
	v_add_u32_e32 v8, 0x600, v16
	v_ashrrev_i32_e32 v8, 4, v8
	v_ashrrev_i32_e32 v9, 31, v8
	v_lshl_add_u64 v[14:15], s[14:15], 0, v[8:9]
	v_lshlrev_b64 v[14:15], 11, v[14:15]
	v_lshl_add_u64 v[14:15], v[4:5], 0, v[14:15]
	v_add_u32_e32 v9, 0x800, v16
	v_ashrrev_i32_e32 v12, 4, v9
	v_ashrrev_i32_e32 v13, 31, v12
	v_lshl_add_u64 v[14:15], s[14:15], 0, v[12:13]
	v_mad_u64_u32 v[8:9], s[20:21], v8, s54, v[10:11]
	v_lshlrev_b64 v[14:15], 11, v[14:15]
	v_lshl_add_u64 v[14:15], v[4:5], 0, v[14:15]
	v_mad_u64_u32 v[12:13], s[20:21], v12, s54, v[10:11]
	v_add_u32_e32 v8, 0xa00, v16
	v_ashrrev_i32_e32 v8, 4, v8
	v_ashrrev_i32_e32 v9, 31, v8
	v_lshl_add_u64 v[14:15], s[14:15], 0, v[8:9]
	v_lshlrev_b64 v[14:15], 11, v[14:15]
	v_lshl_add_u64 v[14:15], v[4:5], 0, v[14:15]
	v_add_u32_e32 v9, 0xc00, v16
	v_ashrrev_i32_e32 v12, 4, v9
	v_ashrrev_i32_e32 v13, 31, v12
	v_lshl_add_u64 v[14:15], s[14:15], 0, v[12:13]
	v_mad_u64_u32 v[8:9], s[20:21], v8, s54, v[10:11]
	v_lshlrev_b64 v[14:15], 11, v[14:15]
	v_lshl_add_u64 v[14:15], v[4:5], 0, v[14:15]
	v_mad_u64_u32 v[12:13], s[20:21], v12, s54, v[10:11]
	v_add_u32_e32 v8, 0xe00, v16
	v_ashrrev_i32_e32 v8, 4, v8
	v_ashrrev_i32_e32 v9, 31, v8
	v_lshl_add_u64 v[14:15], s[14:15], 0, v[8:9]
	v_lshlrev_b64 v[14:15], 11, v[14:15]
	v_lshl_add_u64 v[4:5], v[4:5], 0, v[14:15]
	v_mad_u64_u32 v[4:5], s[20:21], v8, s54, v[10:11]
	s_add_u32 s20, s4, s35
	s_addc_u32 s21, s5, s30
	s_add_u32 s20, s20, s37
	v_lshlrev_b64 v[12:13], 11, v[6:7]
	s_addc_u32 s21, s21, 0
	v_lshl_add_u64 v[6:7], s[20:21], 0, v[12:13]
	v_lshl_add_u64 v[8:9], v[6:7], 0, v[160:161]
	s_mov_b32 s20, 0xc588000
	v_add_co_u32_e32 v6, vcc, s20, v8
	s_mov_b32 s20, 0xc598000
	s_nop 0
	v_addc_co_u32_e32 v7, vcc, 0, v9, vcc
	v_add_co_u32_e32 v10, vcc, s20, v8
	s_lshl_b32 s30, s31, 5
	s_nop 0
	v_addc_co_u32_e32 v11, vcc, 0, v9, vcc
	s_cmp_gt_i32 s31, 3
	v_and_b32_e32 v161, 63, v16
	global_load_dwordx4 v[66:69], v[6:7], off
	global_load_dwordx4 v[70:73], v[10:11], off
	v_lshlrev_b32_e32 v10, 4, v16
	v_and_b32_e32 v176, 0x70, v10
	v_mov_b64_e32 v[10:11], s[18:19]
	v_mad_i64_i32 v[14:15], s[18:19], v18, s50, v[10:11]
	v_mad_i64_i32 v[10:11], s[18:19], v19, s50, v[10:11]
	v_lshl_add_u64 v[14:15], v[14:15], 0, v[176:177]
	v_lshl_add_u64 v[10:11], v[10:11], 0, v[176:177]
	s_mov_b32 s18, 0xc5a8000
	v_add3_u32 v19, s43, v216, v176
	global_load_dwordx4 v[74:77], v[14:15], off
	global_load_dwordx4 v[78:81], v[10:11], off
	v_add_co_u32_e32 v10, vcc, s18, v8
	v_add3_u32 v15, s43, v215, v176
	s_nop 0
	v_addc_co_u32_e32 v11, vcc, 0, v9, vcc
	s_mov_b32 s18, 0xc5b8000
	v_add_co_u32_e32 v8, vcc, s18, v8
	v_and_b32_e32 v14, 31, v16
	s_nop 0
	v_addc_co_u32_e32 v9, vcc, 0, v9, vcc
	s_mov_b64 s[18:19], -1
	s_cmp_lt_i32 s31, 4
	s_mov_b64 s[20:21], 0
	s_cmp_gt_i32 s31, 3
	s_cbranch_scc0 .Lattn_noprio
	s_setprio 1
; #define LAS __attribute__((address_space(3)))
; template <bool SHIFT> DI void attn_unit(LAS unsigned char* lds, const bf16_t* Qb, const bf16_t* Kb, const bf16_t* Vt, bf16_t* concat,
;                   int b, int h, int qt, float shift2, float lam, int lam_init_bits, const float* subln_g) {
;     ...
;     for (int i = 0; i < 8; ++i) { const int id = i * 512 + tid, row = id >> 4, c = id & 15;
;         const u32x4 v = *(const u32x4*)(Qb + (rowbase + q0 + row) * 1024 + h * 128 + c * 8);
;         *(LAS u32x4*)(lds + Q_OFF + row * QP + c * 16) = v; }
;     u32x4 sg0, sg1;
;     sg0 = *(const u32x4*)(kg + (size_t)(krow0) * 1024 + kc * 8); sg1 = *(const u32x4*)(kg + (size_t)(krow0 + 32) * 1024 + kc * 8);
;     *(LAS u32x4*)(lds + K_OFF + krow0 * QP + kc * 16) = sg0; *(LAS u32x4*)(lds + K_OFF + (krow0 + 32) * QP + kc * 16) = sg1;
;     sg0 = *(const u32x4*)(vg + (size_t)(vrow0) * TPB + vc * 8); sg1 = *(const u32x4*)(vg + (size_t)(vrow0 + 64) * TPB + vc * 8);
;     *(LAS u32x4*)(lds + V_OFF + vrow0 * VP + vc * 16) = sg0; *(LAS u32x4*)(lds + V_OFF + (vrow0 + 64) * VP + vc * 16) = sg1;
;     if (nkt > 1) { sg0 = *(const u32x4*)(kg + (size_t)(64 + krow0) * 1024 + kc * 8); sg1 = *(const u32x4*)(kg + (size_t)(64 + krow0 + 32) * 1024 + kc * 8); }
;     __syncthreads();
;     f32x16 OT[2][4];
; #pragma unroll
;     for (int m = 0; m < 2; ++m)
; #pragma unroll
;         for (int t = 0; t < 4; ++t)
; #pragma unroll
;             for (int i = 0; i < 16; ++i) OT[m][t][i] = 0.f;
;     float lsum[2] = {0.f, 0.f};
;     const LAS unsigned char* qrow = lds + Q_OFF + (32 * wid + r) * QP + hh * 16;
;     ...
;     const bool lag = wid >= 4;
;     bf16x8 Pc[2][2];
; #pragma unroll
;     for (int m = 0; m < 2; ++m)
; #pragma unroll
;         for (int g = 0; g < 2; ++g) { u32x4 z = {0u, 0u, 0u, 0u}; Pc[m][g] = __builtin_bit_cast(bf16x8, z); }
;     const LAS unsigned char* vold = lds + V_OFF + r * VP + hh * 16;
;     int vcur = 0;
.Lattn_noprio:
	s_cmp_eq_u32 s23, 0
	s_cselect_b32 s35, 2, 0x82
	s_lshl_b32 s23, s35, 17
	s_or_b32 s36, s23, 0x20000
	v_mul_u32_u24_e32 v237, 0x110, v14
	v_add3_u32 v212, s47, v237, v163
	global_load_dwordx4 v[144:147], v[10:11], off
	global_load_dwordx4 v[148:151], v[8:9], off
	s_waitcnt vmcnt(2)
	ds_write_b128 v82, v[32:35]
	ds_write_b128 v82, v[36:39] offset:8704
	ds_write_b128 v82, v[40:43] offset:17408
	ds_write_b128 v82, v[44:47] offset:26112
	ds_write_b128 v82, v[48:51] offset:34816
	ds_write_b128 v82, v[52:55] offset:43520
	ds_write_b128 v82, v[56:59] offset:52224
	ds_write_b128 v82, v[60:63] offset:60928
	ds_write_b128 v20, v[66:69]
	ds_write_b128 v21, v[70:73]
	ds_write_b128 v15, v[74:77]
	ds_write_b128 v19, v[78:81]
	v_or_b32_e32 v2, s30, v14
	v_mul_lo_u32 v2, v2, s54
	v_add_u32_e32 v16, 0, v2
	v_mul_u32_u24_e32 v2, 0x90, v14
	v_add3_u32 v213, s43, v2, v163
	v_mov_b32_e32 v2, 0x1080000
	v_mad_i64_i32 v[2:3], s[22:23], s22, v2, v[12:13]
	v_or3_b32 v2, v2, s37, v160
	v_mad_i64_i32 v[0:1], s[72:73], v18, s50, 0
	v_lshl_add_u64 v[166:167], s[4:5], 0, v[2:3]
	v_mov_b32_e32 v2, 0x210000
	v_mad_i64_i32 v[0:1], s[4:5], s34, v2, v[0:1]
	v_or_b32_e32 v0, v0, v176
	v_lshl_add_u64 v[0:1], s[6:7], 0, v[0:1]
	s_mov_b64 s[4:5], 0x10890080
	v_mov_b32_e32 v14, v177
	v_mov_b32_e32 v15, v177
	v_lshl_add_u64 v[168:169], v[0:1], 0, s[4:5]
	v_mov_b32_e32 v0, v177
	v_mov_b32_e32 v1, v177
	v_mov_b32_e32 v2, v177
	v_mov_b32_e32 v3, v177
	v_mov_b32_e32 v4, v177
	v_mov_b32_e32 v5, v177
	v_mov_b32_e32 v6, v177
	v_mov_b32_e32 v7, v177
	v_mov_b32_e32 v8, v177
	v_mov_b32_e32 v9, v177
	v_mov_b32_e32 v10, v177
	v_mov_b32_e32 v11, v177
	v_mov_b32_e32 v12, v177
	v_mov_b32_e32 v13, v177
	v_add_u32_e32 v211, v16, v163
	v_mov_b64_e32 v[62:63], v[14:15]
	v_mov_b64_e32 v[78:79], v[14:15]
	v_mov_b64_e32 v[110:111], v[14:15]
	v_mov_b64_e32 v[30:31], v[14:15]
	v_mov_b64_e32 v[46:47], v[14:15]
	v_mov_b64_e32 v[94:95], v[14:15]
	v_mov_b64_e32 v[126:127], v[14:15]
	s_mov_b64 s[22:23], 0
	v_mov_b64_e32 v[60:61], v[12:13]
	v_mov_b64_e32 v[58:59], v[10:11]
	v_mov_b64_e32 v[56:57], v[8:9]
	v_mov_b64_e32 v[54:55], v[6:7]
	v_mov_b64_e32 v[52:53], v[4:5]
	v_mov_b64_e32 v[50:51], v[2:3]
	v_mov_b64_e32 v[48:49], v[0:1]
	v_mov_b64_e32 v[76:77], v[12:13]
	v_mov_b64_e32 v[74:75], v[10:11]
	v_mov_b64_e32 v[72:73], v[8:9]
	v_mov_b64_e32 v[70:71], v[6:7]
	v_mov_b64_e32 v[68:69], v[4:5]
	v_mov_b64_e32 v[66:67], v[2:3]
	v_mov_b64_e32 v[64:65], v[0:1]
	v_mov_b64_e32 v[108:109], v[12:13]
	v_mov_b64_e32 v[106:107], v[10:11]
	v_mov_b64_e32 v[104:105], v[8:9]
	v_mov_b64_e32 v[102:103], v[6:7]
	v_mov_b64_e32 v[100:101], v[4:5]
	v_mov_b64_e32 v[98:99], v[2:3]
	v_mov_b64_e32 v[96:97], v[0:1]
	v_mov_b64_e32 v[28:29], v[12:13]
	v_mov_b64_e32 v[26:27], v[10:11]
	v_mov_b64_e32 v[24:25], v[8:9]
	v_mov_b64_e32 v[22:23], v[6:7]
	v_mov_b64_e32 v[20:21], v[4:5]
	v_mov_b64_e32 v[18:19], v[2:3]
	v_mov_b64_e32 v[16:17], v[0:1]
	v_mov_b64_e32 v[44:45], v[12:13]
	v_mov_b64_e32 v[42:43], v[10:11]
	v_mov_b64_e32 v[40:41], v[8:9]
	v_mov_b64_e32 v[38:39], v[6:7]
	v_mov_b64_e32 v[36:37], v[4:5]
	v_mov_b64_e32 v[34:35], v[2:3]
	v_mov_b64_e32 v[32:33], v[0:1]
	v_mov_b64_e32 v[92:93], v[12:13]
	v_mov_b64_e32 v[90:91], v[10:11]
	v_mov_b64_e32 v[88:89], v[8:9]
	v_mov_b64_e32 v[86:87], v[6:7]
	v_mov_b64_e32 v[84:85], v[4:5]
	v_mov_b64_e32 v[82:83], v[2:3]
	v_mov_b64_e32 v[80:81], v[0:1]
	v_mov_b64_e32 v[124:125], v[12:13]
	v_mov_b64_e32 v[122:123], v[10:11]
	v_mov_b64_e32 v[120:121], v[8:9]
	v_mov_b64_e32 v[118:119], v[6:7]
	v_mov_b64_e32 v[116:117], v[4:5]
	v_mov_b64_e32 v[114:115], v[2:3]
	v_mov_b64_e32 v[112:113], v[0:1]
	v_mov_b32_e32 v136, v213
	s_mov_b32 s34, 0
	s_waitcnt lgkmcnt(0)
	s_barrier

; template <bool SHIFT> DI void attn_unit(LAS unsigned char* lds, const bf16_t* Qb, const bf16_t* Kb, const bf16_t* Vt, bf16_t* concat,
;                   int b, int h, int qt, float shift2, float lam, int lam_init_bits, const float* subln_g) {
;     ...
;     if (lag) PVH(Pc, vold);
.LBB0_545:
	s_setprio 0
	s_and_b64 vcc, exec, s[4:5]
	s_cbranch_vccnz .LBB0_547
	ds_read_b128 v[136:139], v217 offset:64
	s_waitcnt lgkmcnt(0)
	v_mfma_f32_32x32x16_bf16 v[112:127], v[136:139], v[156:159], v[112:127]
	v_mfma_f32_32x32x16_bf16 v[96:111], v[136:139], v[132:135], v[96:111]
	ds_read_b128 v[136:139], v217 offset:4672
	s_waitcnt lgkmcnt(0)
	v_mfma_f32_32x32x16_bf16 v[80:95], v[136:139], v[156:159], v[80:95]
	v_mfma_f32_32x32x16_bf16 v[64:79], v[136:139], v[132:135], v[64:79]
	ds_read_b128 v[136:139], v217 offset:9280
	s_waitcnt lgkmcnt(0)
	v_mfma_f32_32x32x16_bf16 v[32:47], v[136:139], v[156:159], v[32:47]
	v_mfma_f32_32x32x16_bf16 v[48:63], v[136:139], v[132:135], v[48:63]
	ds_read_b128 v[136:139], v217 offset:13888
	s_waitcnt lgkmcnt(0)
	v_mfma_f32_32x32x16_bf16 v[16:31], v[136:139], v[156:159], v[16:31]
	v_mfma_f32_32x32x16_bf16 v[0:15], v[136:139], v[132:135], v[0:15]
	ds_read_b128 v[132:135], v217 offset:96
	s_waitcnt lgkmcnt(0)
	v_mfma_f32_32x32x16_bf16 v[112:127], v[132:135], v[152:155], v[112:127]
	v_mfma_f32_32x32x16_bf16 v[96:111], v[132:135], v[128:131], v[96:111]
	ds_read_b128 v[132:135], v217 offset:4704
	s_waitcnt lgkmcnt(0)
	v_mfma_f32_32x32x16_bf16 v[80:95], v[132:135], v[152:155], v[80:95]
	v_mfma_f32_32x32x16_bf16 v[64:79], v[132:135], v[128:131], v[64:79]
	ds_read_b128 v[132:135], v217 offset:9312
	s_waitcnt lgkmcnt(0)
	v_mfma_f32_32x32x16_bf16 v[32:47], v[132:135], v[152:155], v[32:47]
	v_mfma_f32_32x32x16_bf16 v[48:63], v[132:135], v[128:131], v[48:63]
	ds_read_b128 v[132:135], v217 offset:13920
	s_waitcnt lgkmcnt(0)
	v_mfma_f32_32x32x16_bf16 v[16:31], v[132:135], v[152:155], v[16:31]
	v_mfma_f32_32x32x16_bf16 v[0:15], v[132:135], v[128:131], v[0:15]
